# GEMM K-loops: LDS-DMA loads issued at the start of each load segment (before the ds_reads), saddr addressing, static prio 1 for waves 0-3, aligned loop heads
# speedup vs baseline: 1.0183x; 1.0183x over previous
; #define PG8_STAGE(bufoff, gbase, voff) do { _Pragma("unroll") for (int _i = 0; _i < 2; ++_i) \
;         __builtin_amdgcn_global_load_lds((const unsigned*)((const char*)(gbase) + (voff)[_i]), (LAS unsigned*)(lds + (bufoff) + ldsw + _i * 8192), 16, 0, 0); } while (0)
; #define PG8_LDA(dst, b, h) do { _Pragma("unroll") for (int m = 0; m < 4; ++m) _Pragma("unroll") for (int k = 0; k < 2; ++k) dst[m][k] = *(const LAS bf16x8*)(lds + PG8_SA(b, h) + aoff + m * 2048 + k * 1024); } while (0)
; #define PG8_LDB(dst, b, h) do { _Pragma("unroll") for (int n = 0; n < 2; ++n) _Pragma("unroll") for (int k = 0; k < 2; ++k) dst[n][k] = *(const LAS bf16x8*)(lds + PG8_SB(b, h) + boff + n * 2048 + k * 1024); } while (0)
; #define PG8_MMA(ai, bj, At, Bt) do { __builtin_amdgcn_s_setprio(1); _Pragma("unroll") for (int m = 0; m < 4; ++m) _Pragma("unroll") for (int n = 0; n < 2; ++n) _Pragma("unroll") for (int k = 0; k < 2; ++k) \
;         acc[ai][bj][m][n] = __builtin_amdgcn_mfma_f32_16x16x32_bf16(Bt[n][k], At[m][k], acc[ai][bj][m][n], 0, 0, 0); __builtin_amdgcn_s_setprio(0); } while (0)
; #define PG8_WAIT_V(n) asm volatile("s_waitcnt vmcnt(" #n ")" ::: "memory")
; #define PG8_WAIT_L(n) asm volatile("s_waitcnt lgkmcnt(" #n ")" ::: "memory")
; #define PG8_BAR __builtin_amdgcn_s_barrier()
; #define PG8_SCHED __builtin_amdgcn_sched_barrier(0)
; template <class Epi, class Sched>
; __device__ __forceinline__ void gemm_phase(LAS unsigned char* lds, const Gemm g, const Sched& S, const Epi& E) {
;     ...
;         for (int t = 0; t < nt; t += 2) {
;             const bool last = (t == nt - 2);
;             const char* a1 = cA + (size_t)(t + 1) * kstep;
;             const char* a2 = last ? nA : cA + (size_t)(t + 2) * kstep; const char* b2 = last ? nB : cB + (size_t)(t + 2) * kstep;
;             const char* a3 = a2 + kstep; const char* b3 = b2 + kstep;
;             PG8_LDB(B0, 0, 0); PG8_LDB(B1, 0, 1); PG8_SCHED; PG8_LDA(At, 0, 0); PG8_STAGE(PG8_SA(1, 1), a1 + hstep, voffA);
;             PG8_WAIT_V(8); PG8_WAIT_L(0); PG8_BAR; PG8_MMA(0, 0, At, B0); PG8_MMA(0, 1, At, B1); PG8_BAR; PG8_SCHED;
;             PG8_LDA(At, 0, 1); PG8_STAGE(PG8_SB(0, 0), b2, voffB); PG8_STAGE(PG8_SB(0, 1), b2 + hstep, voffB); PG8_STAGE(PG8_SA(0, 0), a2, voffA);
;             PG8_WAIT_V(8); PG8_WAIT_L(0); PG8_BAR; PG8_MMA(1, 0, At, B0); PG8_MMA(1, 1, At, B1); PG8_BAR; PG8_SCHED;
.LBB0_503:
	s_add_u32 s16, s14, 0xfffc0080
	s_addc_u32 s17, s15, -1
	s_add_i32 s41, 0, 0x10000
	s_cmp_eq_u32 s40, 12
	s_cselect_b32 s19, s7, s17
	s_cselect_b32 s18, s8, s16
	s_cselect_b32 s17, s12, s33
	s_cselect_b32 s16, s13, s21
	s_add_i32 s51, 0, 0x14000
	v_add_u32_e32 v84, s41, v168
	v_add_u32_e32 v170, s51, v168
	s_add_i32 m0, s26, 0xc000
	s_nop 0
	global_load_lds_dwordx4 v150, s[14:15]
	s_add_i32 m0, s26, 0xe000
	s_nop 0
	global_load_lds_dwordx4 v152, s[14:15]
	ds_read_b128 v[72:75], v84
	ds_read_b128 v[76:79], v84 offset:1024
	ds_read_b128 v[80:83], v84 offset:2048
	ds_read_b128 v[84:87], v84 offset:3072
	ds_read_b128 v[154:157], v170
	ds_read_b128 v[158:161], v170 offset:1024
	ds_read_b128 v[162:165], v170 offset:2048
	ds_read_b128 v[170:173], v170 offset:3072
	ds_read_b128 v[174:177], v169
	ds_read_b128 v[192:195], v169 offset:1024
	ds_read_b128 v[196:199], v169 offset:2048
	ds_read_b128 v[200:203], v169 offset:3072
	ds_read_b128 v[204:207], v169 offset:4096
	ds_read_b128 v[208:211], v169 offset:5120
	ds_read_b128 v[212:215], v169 offset:6144
	ds_read_b128 v[230:233], v169 offset:7168
	s_waitcnt vmcnt(8)
	s_waitcnt lgkmcnt(0)
	s_barrier
	s_waitcnt lgkmcnt(0)
	v_mfma_f32_16x16x32_bf16 v[140:143], v[72:75], v[174:177], v[140:143]
	v_mfma_f32_16x16x32_bf16 v[136:139], v[80:83], v[174:177], v[136:139]
	v_mfma_f32_16x16x32_bf16 v[124:127], v[72:75], v[196:199], v[124:127]
	v_mfma_f32_16x16x32_bf16 v[120:123], v[80:83], v[196:199], v[120:123]
	v_mfma_f32_16x16x32_bf16 v[108:111], v[72:75], v[204:207], v[108:111]
	v_mfma_f32_16x16x32_bf16 v[104:107], v[80:83], v[204:207], v[104:107]
	v_mfma_f32_16x16x32_bf16 v[92:95], v[72:75], v[212:215], v[92:95]
	v_mfma_f32_16x16x32_bf16 v[88:91], v[80:83], v[212:215], v[88:91]
	v_mfma_f32_16x16x32_bf16 v[140:143], v[76:79], v[192:195], v[140:143]
	v_mfma_f32_16x16x32_bf16 v[136:139], v[84:87], v[192:195], v[136:139]
	v_mfma_f32_16x16x32_bf16 v[124:127], v[76:79], v[200:203], v[124:127]
	v_mfma_f32_16x16x32_bf16 v[120:123], v[84:87], v[200:203], v[120:123]
	v_mfma_f32_16x16x32_bf16 v[108:111], v[76:79], v[208:211], v[108:111]
	v_mfma_f32_16x16x32_bf16 v[104:107], v[84:87], v[208:211], v[104:107]
	v_mfma_f32_16x16x32_bf16 v[92:95], v[76:79], v[230:233], v[92:95]
	v_mfma_f32_16x16x32_bf16 v[88:91], v[84:87], v[230:233], v[88:91]
	v_mfma_f32_16x16x32_bf16 v[132:135], v[154:157], v[174:177], v[132:135]
	v_mfma_f32_16x16x32_bf16 v[128:131], v[162:165], v[174:177], v[128:131]
	v_mfma_f32_16x16x32_bf16 v[116:119], v[154:157], v[196:199], v[116:119]
	v_mfma_f32_16x16x32_bf16 v[112:115], v[162:165], v[196:199], v[112:115]
	v_mfma_f32_16x16x32_bf16 v[100:103], v[154:157], v[204:207], v[100:103]
	v_mfma_f32_16x16x32_bf16 v[96:99], v[162:165], v[204:207], v[96:99]
	v_mfma_f32_16x16x32_bf16 v[68:71], v[154:157], v[212:215], v[68:71]
	v_mfma_f32_16x16x32_bf16 v[64:67], v[162:165], v[212:215], v[64:67]
	v_mfma_f32_16x16x32_bf16 v[132:135], v[158:161], v[192:195], v[132:135]
	v_mfma_f32_16x16x32_bf16 v[128:131], v[170:173], v[192:195], v[128:131]
	v_mfma_f32_16x16x32_bf16 v[116:119], v[158:161], v[200:203], v[116:119]
	v_mfma_f32_16x16x32_bf16 v[112:115], v[170:173], v[200:203], v[112:115]
	v_mfma_f32_16x16x32_bf16 v[100:103], v[158:161], v[208:211], v[100:103]
	v_mfma_f32_16x16x32_bf16 v[96:99], v[170:173], v[208:211], v[96:99]
	v_mfma_f32_16x16x32_bf16 v[68:71], v[158:161], v[230:233], v[68:71]
	v_mfma_f32_16x16x32_bf16 v[64:67], v[170:173], v[230:233], v[64:67]
	s_barrier
	s_add_i32 s41, s41, s23
	s_mov_b32 m0, s41
	s_nop 0
	global_load_lds_dwordx4 v184, s[16:17]
	s_add_i32 m0, s41, 0x2000
	s_add_u32 s42, s16, 0x40000
	s_addc_u32 s43, s17, 0
	s_add_i32 s41, s51, s23
	global_load_lds_dwordx4 v148, s[16:17]
	s_mov_b32 m0, s41
	s_nop 0
	global_load_lds_dwordx4 v184, s[42:43]
	s_add_i32 m0, s41, 0x2000
	s_nop 0
	global_load_lds_dwordx4 v148, s[42:43]
	s_mov_b32 m0, s26
	s_nop 0
	global_load_lds_dwordx4 v144, s[18:19]
	s_mov_b32 m0, s27
	s_nop 0
	global_load_lds_dwordx4 v146, s[18:19]
	ds_read_b128 v[174:177], v169 offset:16384
	ds_read_b128 v[192:195], v169 offset:17408
	ds_read_b128 v[196:199], v169 offset:18432
	ds_read_b128 v[200:203], v169 offset:19456
	ds_read_b128 v[204:207], v169 offset:20480
	ds_read_b128 v[208:211], v169 offset:21504
	ds_read_b128 v[212:215], v169 offset:22528
	ds_read_b128 v[230:233], v169 offset:23552
	s_waitcnt vmcnt(8)
	s_waitcnt lgkmcnt(0)
	s_barrier
	s_waitcnt lgkmcnt(0)
	v_mfma_f32_16x16x32_bf16 v[60:63], v[72:75], v[174:177], v[60:63]
	v_mfma_f32_16x16x32_bf16 v[56:59], v[80:83], v[174:177], v[56:59]
	v_mfma_f32_16x16x32_bf16 v[44:47], v[72:75], v[196:199], v[44:47]
	v_mfma_f32_16x16x32_bf16 v[40:43], v[80:83], v[196:199], v[40:43]
	v_mfma_f32_16x16x32_bf16 v[28:31], v[72:75], v[204:207], v[28:31]
	v_mfma_f32_16x16x32_bf16 v[24:27], v[80:83], v[204:207], v[24:27]
	v_mfma_f32_16x16x32_bf16 v[12:15], v[72:75], v[212:215], v[12:15]
	v_mfma_f32_16x16x32_bf16 v[8:11], v[80:83], v[212:215], v[8:11]
	v_mfma_f32_16x16x32_bf16 v[60:63], v[76:79], v[192:195], v[60:63]
	v_mfma_f32_16x16x32_bf16 v[56:59], v[84:87], v[192:195], v[56:59]
	v_mfma_f32_16x16x32_bf16 v[44:47], v[76:79], v[200:203], v[44:47]
	v_mfma_f32_16x16x32_bf16 v[40:43], v[84:87], v[200:203], v[40:43]
	v_mfma_f32_16x16x32_bf16 v[28:31], v[76:79], v[208:211], v[28:31]
	v_mfma_f32_16x16x32_bf16 v[24:27], v[84:87], v[208:211], v[24:27]
	v_mfma_f32_16x16x32_bf16 v[12:15], v[76:79], v[230:233], v[12:15]
	v_mfma_f32_16x16x32_bf16 v[8:11], v[84:87], v[230:233], v[8:11]
	v_mfma_f32_16x16x32_bf16 v[52:55], v[154:157], v[174:177], v[52:55]
	v_mfma_f32_16x16x32_bf16 v[48:51], v[162:165], v[174:177], v[48:51]
	v_mfma_f32_16x16x32_bf16 v[36:39], v[154:157], v[196:199], v[36:39]
	v_mfma_f32_16x16x32_bf16 v[32:35], v[162:165], v[196:199], v[32:35]
	v_mfma_f32_16x16x32_bf16 v[20:23], v[154:157], v[204:207], v[20:23]
	v_mfma_f32_16x16x32_bf16 v[16:19], v[162:165], v[204:207], v[16:19]
	v_mfma_f32_16x16x32_bf16 v[4:7], v[154:157], v[212:215], v[4:7]
	v_mfma_f32_16x16x32_bf16 v[0:3], v[162:165], v[212:215], v[0:3]
	v_mfma_f32_16x16x32_bf16 v[52:55], v[158:161], v[192:195], v[52:55]
	v_mfma_f32_16x16x32_bf16 v[48:51], v[170:173], v[192:195], v[48:51]
	v_mfma_f32_16x16x32_bf16 v[36:39], v[158:161], v[200:203], v[36:39]
	v_mfma_f32_16x16x32_bf16 v[32:35], v[170:173], v[200:203], v[32:35]
	v_mfma_f32_16x16x32_bf16 v[20:23], v[158:161], v[208:211], v[20:23]
	v_mfma_f32_16x16x32_bf16 v[16:19], v[170:173], v[208:211], v[16:19]
	v_mfma_f32_16x16x32_bf16 v[4:7], v[158:161], v[230:233], v[4:7]
	v_mfma_f32_16x16x32_bf16 v[0:3], v[170:173], v[230:233], v[0:3]
	s_barrier
; #define PG8_STAGE(bufoff, gbase, voff) do { _Pragma("unroll") for (int _i = 0; _i < 2; ++_i) \
;         __builtin_amdgcn_global_load_lds((const unsigned*)((const char*)(gbase) + (voff)[_i]), (LAS unsigned*)(lds + (bufoff) + ldsw + _i * 8192), 16, 0, 0); } while (0)
; #define PG8_LDA(dst, b, h) do { _Pragma("unroll") for (int m = 0; m < 4; ++m) _Pragma("unroll") for (int k = 0; k < 2; ++k) dst[m][k] = *(const LAS bf16x8*)(lds + PG8_SA(b, h) + aoff + m * 2048 + k * 1024); } while (0)
; #define PG8_LDB(dst, b, h) do { _Pragma("unroll") for (int n = 0; n < 2; ++n) _Pragma("unroll") for (int k = 0; k < 2; ++k) dst[n][k] = *(const LAS bf16x8*)(lds + PG8_SB(b, h) + boff + n * 2048 + k * 1024); } while (0)
; #define PG8_MMA(ai, bj, At, Bt) do { __builtin_amdgcn_s_setprio(1); _Pragma("unroll") for (int m = 0; m < 4; ++m) _Pragma("unroll") for (int n = 0; n < 2; ++n) _Pragma("unroll") for (int k = 0; k < 2; ++k) \
;         acc[ai][bj][m][n] = __builtin_amdgcn_mfma_f32_16x16x32_bf16(Bt[n][k], At[m][k], acc[ai][bj][m][n], 0, 0, 0); __builtin_amdgcn_s_setprio(0); } while (0)
; #define PG8_WAIT_V(n) asm volatile("s_waitcnt vmcnt(" #n ")" ::: "memory")
; #define PG8_WAIT_L(n) asm volatile("s_waitcnt lgkmcnt(" #n ")" ::: "memory")
; #define PG8_BAR __builtin_amdgcn_s_barrier()
; #define PG8_SCHED __builtin_amdgcn_sched_barrier(0)
; template <class Epi, class Sched>
; __device__ __forceinline__ void gemm_phase(LAS unsigned char* lds, const Gemm g, const Sched& S, const Epi& E) {
;     ...
;             PG8_LDB(B0, 1, 0); PG8_LDB(B1, 1, 1); PG8_SCHED; PG8_LDA(At, 1, 0); PG8_STAGE(PG8_SA(0, 1), a2 + hstep, voffA);
;             PG8_WAIT_V(8); PG8_WAIT_L(0); PG8_BAR; PG8_MMA(0, 0, At, B0); PG8_MMA(0, 1, At, B1); PG8_BAR; PG8_SCHED;
;             PG8_LDA(At, 1, 1); PG8_STAGE(PG8_SB(1, 0), b3, voffB); PG8_STAGE(PG8_SB(1, 1), b3 + hstep, voffB); PG8_STAGE(PG8_SA(1, 0), a3, voffA);
;             PG8_WAIT_V(8); PG8_WAIT_L(0); PG8_BAR; PG8_MMA(1, 0, At, B0); PG8_MMA(1, 1, At, B1); PG8_BAR; PG8_SCHED;
;         }
;         if (wr == 0) PG8_BAR;
	s_add_i32 s41, 0, 0x18000
	s_add_i32 s42, 0, 0x1c000
	v_add_u32_e32 v84, s41, v168
	v_add_u32_e32 v170, s42, v168
	s_add_u32 s18, s18, 0x40000
	s_addc_u32 s19, s19, 0
	s_mov_b32 m0, s28
	s_nop 0
	global_load_lds_dwordx4 v144, s[18:19]
	s_mov_b32 m0, s29
	s_nop 0
	global_load_lds_dwordx4 v146, s[18:19]
	ds_read_b128 v[72:75], v84
	ds_read_b128 v[76:79], v84 offset:1024
	ds_read_b128 v[80:83], v84 offset:2048
	ds_read_b128 v[84:87], v84 offset:3072
	ds_read_b128 v[154:157], v170
	ds_read_b128 v[158:161], v170 offset:1024
	ds_read_b128 v[162:165], v170 offset:2048
	ds_read_b128 v[170:173], v170 offset:3072
	ds_read_b128 v[174:177], v169 offset:32768
	ds_read_b128 v[192:195], v169 offset:33792
	ds_read_b128 v[196:199], v169 offset:34816
	ds_read_b128 v[200:203], v169 offset:35840
	ds_read_b128 v[204:207], v169 offset:36864
	ds_read_b128 v[208:211], v169 offset:37888
	ds_read_b128 v[212:215], v169 offset:38912
	ds_read_b128 v[230:233], v169 offset:39936
	s_waitcnt vmcnt(8)
	s_waitcnt lgkmcnt(0)
	s_barrier
	s_waitcnt lgkmcnt(0)
	v_mfma_f32_16x16x32_bf16 v[140:143], v[72:75], v[174:177], v[140:143]
	v_mfma_f32_16x16x32_bf16 v[136:139], v[80:83], v[174:177], v[136:139]
	v_mfma_f32_16x16x32_bf16 v[124:127], v[72:75], v[196:199], v[124:127]
	v_mfma_f32_16x16x32_bf16 v[120:123], v[80:83], v[196:199], v[120:123]
	v_mfma_f32_16x16x32_bf16 v[108:111], v[72:75], v[204:207], v[108:111]
	v_mfma_f32_16x16x32_bf16 v[104:107], v[80:83], v[204:207], v[104:107]
	v_mfma_f32_16x16x32_bf16 v[92:95], v[72:75], v[212:215], v[92:95]
	v_mfma_f32_16x16x32_bf16 v[88:91], v[80:83], v[212:215], v[88:91]
	v_mfma_f32_16x16x32_bf16 v[140:143], v[76:79], v[192:195], v[140:143]
	v_mfma_f32_16x16x32_bf16 v[136:139], v[84:87], v[192:195], v[136:139]
	v_mfma_f32_16x16x32_bf16 v[124:127], v[76:79], v[200:203], v[124:127]
	v_mfma_f32_16x16x32_bf16 v[120:123], v[84:87], v[200:203], v[120:123]
	v_mfma_f32_16x16x32_bf16 v[108:111], v[76:79], v[208:211], v[108:111]
	v_mfma_f32_16x16x32_bf16 v[104:107], v[84:87], v[208:211], v[104:107]
	v_mfma_f32_16x16x32_bf16 v[92:95], v[76:79], v[230:233], v[92:95]
	v_mfma_f32_16x16x32_bf16 v[88:91], v[84:87], v[230:233], v[88:91]
	v_mfma_f32_16x16x32_bf16 v[132:135], v[154:157], v[174:177], v[132:135]
	v_mfma_f32_16x16x32_bf16 v[128:131], v[162:165], v[174:177], v[128:131]
	v_mfma_f32_16x16x32_bf16 v[116:119], v[154:157], v[196:199], v[116:119]
	v_mfma_f32_16x16x32_bf16 v[112:115], v[162:165], v[196:199], v[112:115]
	v_mfma_f32_16x16x32_bf16 v[100:103], v[154:157], v[204:207], v[100:103]
	v_mfma_f32_16x16x32_bf16 v[96:99], v[162:165], v[204:207], v[96:99]
	v_mfma_f32_16x16x32_bf16 v[68:71], v[154:157], v[212:215], v[68:71]
	v_mfma_f32_16x16x32_bf16 v[64:67], v[162:165], v[212:215], v[64:67]
	v_mfma_f32_16x16x32_bf16 v[132:135], v[158:161], v[192:195], v[132:135]
	v_mfma_f32_16x16x32_bf16 v[128:131], v[170:173], v[192:195], v[128:131]
	v_mfma_f32_16x16x32_bf16 v[116:119], v[158:161], v[200:203], v[116:119]
	v_mfma_f32_16x16x32_bf16 v[112:115], v[170:173], v[200:203], v[112:115]
	v_mfma_f32_16x16x32_bf16 v[100:103], v[158:161], v[208:211], v[100:103]
	v_mfma_f32_16x16x32_bf16 v[96:99], v[170:173], v[208:211], v[96:99]
	v_mfma_f32_16x16x32_bf16 v[68:71], v[158:161], v[230:233], v[68:71]
	v_mfma_f32_16x16x32_bf16 v[64:67], v[170:173], v[230:233], v[64:67]
	s_barrier
	s_add_u32 s16, s16, 0x80
	s_addc_u32 s17, s17, 0
	s_add_i32 m0, s41, s23
	s_nop 0
	global_load_lds_dwordx4 v184, s[16:17]
	s_add_i32 m0, m0, 0x2000
	s_nop 0
	global_load_lds_dwordx4 v148, s[16:17]
	s_add_u32 s16, s16, 0x40000
	s_addc_u32 s17, s17, 0
	s_add_i32 m0, s42, s23
	s_nop 0
	global_load_lds_dwordx4 v184, s[16:17]
	s_add_i32 m0, m0, 0x2000
	s_nop 0
	global_load_lds_dwordx4 v148, s[16:17]
	s_add_u32 s18, s18, 0xfffc0080
	s_addc_u32 s19, s19, -1
	s_mov_b32 m0, s34
	s_nop 0
	global_load_lds_dwordx4 v144, s[18:19]
	s_mov_b32 m0, s35
	s_nop 0
	global_load_lds_dwordx4 v146, s[18:19]
	ds_read_b128 v[174:177], v169 offset:49152
	ds_read_b128 v[192:195], v169 offset:50176
	ds_read_b128 v[196:199], v169 offset:51200
	ds_read_b128 v[200:203], v169 offset:52224
	ds_read_b128 v[204:207], v169 offset:53248
	ds_read_b128 v[208:211], v169 offset:54272
	ds_read_b128 v[212:215], v169 offset:55296
	ds_read_b128 v[230:233], v169 offset:56320
	s_waitcnt vmcnt(8)
	s_waitcnt lgkmcnt(0)
	s_barrier
	s_waitcnt lgkmcnt(0)
	v_mfma_f32_16x16x32_bf16 v[60:63], v[72:75], v[174:177], v[60:63]
	v_mfma_f32_16x16x32_bf16 v[56:59], v[80:83], v[174:177], v[56:59]
	v_mfma_f32_16x16x32_bf16 v[44:47], v[72:75], v[196:199], v[44:47]
	v_mfma_f32_16x16x32_bf16 v[40:43], v[80:83], v[196:199], v[40:43]
	v_mfma_f32_16x16x32_bf16 v[28:31], v[72:75], v[204:207], v[28:31]
	v_mfma_f32_16x16x32_bf16 v[24:27], v[80:83], v[204:207], v[24:27]
	v_mfma_f32_16x16x32_bf16 v[12:15], v[72:75], v[212:215], v[12:15]
	v_mfma_f32_16x16x32_bf16 v[8:11], v[80:83], v[212:215], v[8:11]
	v_mfma_f32_16x16x32_bf16 v[60:63], v[76:79], v[192:195], v[60:63]
	v_mfma_f32_16x16x32_bf16 v[56:59], v[84:87], v[192:195], v[56:59]
	v_mfma_f32_16x16x32_bf16 v[44:47], v[76:79], v[200:203], v[44:47]
	v_mfma_f32_16x16x32_bf16 v[40:43], v[84:87], v[200:203], v[40:43]
	v_mfma_f32_16x16x32_bf16 v[28:31], v[76:79], v[208:211], v[28:31]
	v_mfma_f32_16x16x32_bf16 v[24:27], v[84:87], v[208:211], v[24:27]
	v_mfma_f32_16x16x32_bf16 v[12:15], v[76:79], v[230:233], v[12:15]
	v_mfma_f32_16x16x32_bf16 v[8:11], v[84:87], v[230:233], v[8:11]
	v_mfma_f32_16x16x32_bf16 v[52:55], v[154:157], v[174:177], v[52:55]
	v_mfma_f32_16x16x32_bf16 v[48:51], v[162:165], v[174:177], v[48:51]
	v_mfma_f32_16x16x32_bf16 v[36:39], v[154:157], v[196:199], v[36:39]
	v_mfma_f32_16x16x32_bf16 v[32:35], v[162:165], v[196:199], v[32:35]
	v_mfma_f32_16x16x32_bf16 v[20:23], v[154:157], v[204:207], v[20:23]
	v_mfma_f32_16x16x32_bf16 v[16:19], v[162:165], v[204:207], v[16:19]
	v_mfma_f32_16x16x32_bf16 v[4:7], v[154:157], v[212:215], v[4:7]
	v_mfma_f32_16x16x32_bf16 v[0:3], v[162:165], v[212:215], v[0:3]
	v_mfma_f32_16x16x32_bf16 v[52:55], v[158:161], v[192:195], v[52:55]
	v_mfma_f32_16x16x32_bf16 v[48:51], v[170:173], v[192:195], v[48:51]
	v_mfma_f32_16x16x32_bf16 v[36:39], v[158:161], v[200:203], v[36:39]
	v_mfma_f32_16x16x32_bf16 v[32:35], v[170:173], v[200:203], v[32:35]
	v_mfma_f32_16x16x32_bf16 v[20:23], v[158:161], v[208:211], v[20:23]
	v_mfma_f32_16x16x32_bf16 v[16:19], v[170:173], v[208:211], v[16:19]
	v_mfma_f32_16x16x32_bf16 v[4:7], v[158:161], v[230:233], v[4:7]
	v_mfma_f32_16x16x32_bf16 v[0:3], v[170:173], v[230:233], v[0:3]
	s_barrier
	s_add_i32 s40, s40, 2
	s_add_u32 s14, s14, 0x100
	s_addc_u32 s15, s15, 0
	s_add_u32 s21, s21, 0x100
	s_addc_u32 s33, s33, 0
	s_cmp_gt_u32 s40, 13
	s_cbranch_scc0 .LBB0_503
	s_setprio 0
	s_and_b64 vcc, exec, s[48:49]
	s_cbranch_vccz .LBB0_506
	s_barrier

; #define PG8_STAGE(bufoff, gbase, voff) do { _Pragma("unroll") for (int _i = 0; _i < 2; ++_i) \
;         __builtin_amdgcn_global_load_lds((const unsigned*)((const char*)(gbase) + (voff)[_i]), (LAS unsigned*)(lds + (bufoff) + ldsw + _i * 8192), 16, 0, 0); } while (0)
; #define PG8_LDA(dst, b, h) do { _Pragma("unroll") for (int m = 0; m < 4; ++m) _Pragma("unroll") for (int k = 0; k < 2; ++k) dst[m][k] = *(const LAS bf16x8*)(lds + PG8_SA(b, h) + aoff + m * 2048 + k * 1024); } while (0)
; #define PG8_LDB(dst, b, h) do { _Pragma("unroll") for (int n = 0; n < 2; ++n) _Pragma("unroll") for (int k = 0; k < 2; ++k) dst[n][k] = *(const LAS bf16x8*)(lds + PG8_SB(b, h) + boff + n * 2048 + k * 1024); } while (0)
; #define PG8_MMA(ai, bj, At, Bt) do { __builtin_amdgcn_s_setprio(1); _Pragma("unroll") for (int m = 0; m < 4; ++m) _Pragma("unroll") for (int n = 0; n < 2; ++n) _Pragma("unroll") for (int k = 0; k < 2; ++k) \
;         acc[ai][bj][m][n] = __builtin_amdgcn_mfma_f32_16x16x32_bf16(Bt[n][k], At[m][k], acc[ai][bj][m][n], 0, 0, 0); __builtin_amdgcn_s_setprio(0); } while (0)
; #define PG8_WAIT_V(n) asm volatile("s_waitcnt vmcnt(" #n ")" ::: "memory")
; #define PG8_WAIT_L(n) asm volatile("s_waitcnt lgkmcnt(" #n ")" ::: "memory")
; #define PG8_BAR __builtin_amdgcn_s_barrier()
; #define PG8_SCHED __builtin_amdgcn_sched_barrier(0)
; template <class Epi, class Sched>
; __device__ __forceinline__ void gemm_phase(LAS unsigned char* lds, const Gemm g, const Sched& S, const Epi& E) {
;     ...
;         for (int t = 0; t < nt; t += 2) {
;             const bool last = (t == nt - 2);
;             const char* a1 = cA + (size_t)(t + 1) * kstep;
;             const char* a2 = last ? nA : cA + (size_t)(t + 2) * kstep; const char* b2 = last ? nB : cB + (size_t)(t + 2) * kstep;
;             const char* a3 = a2 + kstep; const char* b3 = b2 + kstep;
;             PG8_LDB(B0, 0, 0); PG8_LDB(B1, 0, 1); PG8_SCHED; PG8_LDA(At, 0, 0); PG8_STAGE(PG8_SA(1, 1), a1 + hstep, voffA);
;             PG8_WAIT_V(8); PG8_WAIT_L(0); PG8_BAR; PG8_MMA(0, 0, At, B0); PG8_MMA(0, 1, At, B1); PG8_BAR; PG8_SCHED;
;             PG8_LDA(At, 0, 1); PG8_STAGE(PG8_SB(0, 0), b2, voffB); PG8_STAGE(PG8_SB(0, 1), b2 + hstep, voffB); PG8_STAGE(PG8_SA(0, 0), a2, voffA);
;             PG8_WAIT_V(8); PG8_WAIT_L(0); PG8_BAR; PG8_MMA(1, 0, At, B0); PG8_MMA(1, 1, At, B1); PG8_BAR; PG8_SCHED;
.LBB0_599:
	s_add_i32 s19, s17, 2
	s_add_u32 s14, s6, 0x80
	s_addc_u32 s15, s7, 0
	s_add_i32 s33, 0, 0x10000
	s_cmp_eq_u32 s12, s17
	s_cselect_b32 s15, s1, s15
	s_cselect_b32 s14, s0, s14
	s_cselect_b32 s43, s65, s16
	s_cselect_b32 s42, s64, s13
	s_add_i32 s17, 0, 0x14000
	v_add_u32_e32 v140, s33, v231
	v_add_u32_e32 v156, s17, v231
	s_waitcnt lgkmcnt(0)
	s_add_i32 m0, s29, 0xc000
	s_nop 0
	global_load_lds_dwordx4 v198, s[6:7]
	s_add_i32 m0, s29, 0xe000
	s_nop 0
	global_load_lds_dwordx4 v200, s[6:7]
	ds_read_b128 v[128:131], v140
	ds_read_b128 v[132:135], v140 offset:1024
	ds_read_b128 v[136:139], v140 offset:2048
	ds_read_b128 v[140:143], v140 offset:3072
	ds_read_b128 v[144:147], v156
	ds_read_b128 v[148:151], v156 offset:1024
	ds_read_b128 v[152:155], v156 offset:2048
	ds_read_b128 v[156:159], v156 offset:3072
	ds_read_b128 v[160:163], v232
	ds_read_b128 v[164:167], v232 offset:1024
	ds_read_b128 v[168:171], v232 offset:2048
	ds_read_b128 v[172:175], v232 offset:3072
	ds_read_b128 v[176:179], v232 offset:4096
	ds_read_b128 v[202:205], v232 offset:5120
	ds_read_b128 v[206:209], v232 offset:6144
	ds_read_b128 v[210:213], v232 offset:7168
	s_waitcnt vmcnt(8)
	s_waitcnt lgkmcnt(0)
	s_barrier
	s_waitcnt lgkmcnt(0)
	v_mfma_f32_16x16x32_bf16 v[124:127], v[128:131], v[160:163], v[124:127]
	v_mfma_f32_16x16x32_bf16 v[120:123], v[136:139], v[160:163], v[120:123]
	v_mfma_f32_16x16x32_bf16 v[116:119], v[128:131], v[168:171], v[116:119]
	v_mfma_f32_16x16x32_bf16 v[112:115], v[136:139], v[168:171], v[112:115]
	v_mfma_f32_16x16x32_bf16 v[104:107], v[128:131], v[176:179], v[104:107]
	v_mfma_f32_16x16x32_bf16 v[96:99], v[136:139], v[176:179], v[96:99]
	v_mfma_f32_16x16x32_bf16 v[88:91], v[128:131], v[206:209], v[88:91]
	v_mfma_f32_16x16x32_bf16 v[80:83], v[136:139], v[206:209], v[80:83]
	v_mfma_f32_16x16x32_bf16 v[124:127], v[132:135], v[164:167], v[124:127]
	v_mfma_f32_16x16x32_bf16 v[120:123], v[140:143], v[164:167], v[120:123]
	v_mfma_f32_16x16x32_bf16 v[116:119], v[132:135], v[172:175], v[116:119]
	v_mfma_f32_16x16x32_bf16 v[112:115], v[140:143], v[172:175], v[112:115]
	v_mfma_f32_16x16x32_bf16 v[104:107], v[132:135], v[202:205], v[104:107]
	v_mfma_f32_16x16x32_bf16 v[96:99], v[140:143], v[202:205], v[96:99]
	v_mfma_f32_16x16x32_bf16 v[88:91], v[132:135], v[210:213], v[88:91]
	v_mfma_f32_16x16x32_bf16 v[80:83], v[140:143], v[210:213], v[80:83]
	v_mfma_f32_16x16x32_bf16 v[108:111], v[144:147], v[160:163], v[108:111]
	v_mfma_f32_16x16x32_bf16 v[100:103], v[152:155], v[160:163], v[100:103]
	v_mfma_f32_16x16x32_bf16 v[92:95], v[144:147], v[168:171], v[92:95]
	v_mfma_f32_16x16x32_bf16 v[84:87], v[152:155], v[168:171], v[84:87]
	v_mfma_f32_16x16x32_bf16 v[76:79], v[144:147], v[176:179], v[76:79]
	v_mfma_f32_16x16x32_bf16 v[72:75], v[152:155], v[176:179], v[72:75]
	v_mfma_f32_16x16x32_bf16 v[68:71], v[144:147], v[206:209], v[68:71]
	v_mfma_f32_16x16x32_bf16 v[64:67], v[152:155], v[206:209], v[64:67]
	v_mfma_f32_16x16x32_bf16 v[108:111], v[148:151], v[164:167], v[108:111]
	v_mfma_f32_16x16x32_bf16 v[100:103], v[156:159], v[164:167], v[100:103]
	v_mfma_f32_16x16x32_bf16 v[92:95], v[148:151], v[172:175], v[92:95]
	v_mfma_f32_16x16x32_bf16 v[84:87], v[156:159], v[172:175], v[84:87]
	v_mfma_f32_16x16x32_bf16 v[76:79], v[148:151], v[202:205], v[76:79]
	v_mfma_f32_16x16x32_bf16 v[72:75], v[156:159], v[202:205], v[72:75]
	v_mfma_f32_16x16x32_bf16 v[68:71], v[148:151], v[210:213], v[68:71]
	v_mfma_f32_16x16x32_bf16 v[64:67], v[156:159], v[210:213], v[64:67]
	s_barrier
	s_add_i32 s33, s33, s28
	s_mov_b32 m0, s33
	s_nop 0
	global_load_lds_dwordx4 v184, s[42:43]
	s_add_i32 m0, s33, 0x2000
	s_nop 0
	global_load_lds_dwordx4 v196, s[42:43]
	s_add_u32 s42, s42, s54
	s_addc_u32 s43, s43, 0
	s_add_i32 s17, s17, s28
	s_mov_b32 m0, s17
	s_nop 0
	global_load_lds_dwordx4 v184, s[42:43]
	s_add_i32 m0, s17, 0x2000
	s_nop 0
	global_load_lds_dwordx4 v196, s[42:43]
	s_mov_b32 m0, s29
	s_nop 0
	global_load_lds_dwordx4 v192, s[14:15]
	s_mov_b32 m0, s30
	s_nop 0
	global_load_lds_dwordx4 v194, s[14:15]
	ds_read_b128 v[160:163], v232 offset:16384
	ds_read_b128 v[164:167], v232 offset:17408
	ds_read_b128 v[168:171], v232 offset:18432
	ds_read_b128 v[172:175], v232 offset:19456
	ds_read_b128 v[176:179], v232 offset:20480
	ds_read_b128 v[202:205], v232 offset:21504
	ds_read_b128 v[206:209], v232 offset:22528
	ds_read_b128 v[210:213], v232 offset:23552
	s_waitcnt vmcnt(8)
	s_waitcnt lgkmcnt(0)
	s_barrier
	s_waitcnt lgkmcnt(0)
	v_mfma_f32_16x16x32_bf16 v[60:63], v[128:131], v[160:163], v[60:63]
	v_mfma_f32_16x16x32_bf16 v[56:59], v[136:139], v[160:163], v[56:59]
	v_mfma_f32_16x16x32_bf16 v[52:55], v[128:131], v[168:171], v[52:55]
	v_mfma_f32_16x16x32_bf16 v[48:51], v[136:139], v[168:171], v[48:51]
	v_mfma_f32_16x16x32_bf16 v[36:39], v[128:131], v[176:179], v[36:39]
	v_mfma_f32_16x16x32_bf16 v[32:35], v[136:139], v[176:179], v[32:35]
	v_mfma_f32_16x16x32_bf16 v[20:23], v[128:131], v[206:209], v[20:23]
	v_mfma_f32_16x16x32_bf16 v[16:19], v[136:139], v[206:209], v[16:19]
	v_mfma_f32_16x16x32_bf16 v[60:63], v[132:135], v[164:167], v[60:63]
	v_mfma_f32_16x16x32_bf16 v[56:59], v[140:143], v[164:167], v[56:59]
	v_mfma_f32_16x16x32_bf16 v[52:55], v[132:135], v[172:175], v[52:55]
	v_mfma_f32_16x16x32_bf16 v[48:51], v[140:143], v[172:175], v[48:51]
	v_mfma_f32_16x16x32_bf16 v[36:39], v[132:135], v[202:205], v[36:39]
	v_mfma_f32_16x16x32_bf16 v[32:35], v[140:143], v[202:205], v[32:35]
	v_mfma_f32_16x16x32_bf16 v[20:23], v[132:135], v[210:213], v[20:23]
	v_mfma_f32_16x16x32_bf16 v[16:19], v[140:143], v[210:213], v[16:19]
	v_mfma_f32_16x16x32_bf16 v[44:47], v[144:147], v[160:163], v[44:47]
	v_mfma_f32_16x16x32_bf16 v[40:43], v[152:155], v[160:163], v[40:43]
	v_mfma_f32_16x16x32_bf16 v[28:31], v[144:147], v[168:171], v[28:31]
	v_mfma_f32_16x16x32_bf16 v[24:27], v[152:155], v[168:171], v[24:27]
	v_mfma_f32_16x16x32_bf16 v[12:15], v[144:147], v[176:179], v[12:15]
	v_mfma_f32_16x16x32_bf16 v[8:11], v[152:155], v[176:179], v[8:11]
	v_mfma_f32_16x16x32_bf16 v[4:7], v[144:147], v[206:209], v[4:7]
	v_mfma_f32_16x16x32_bf16 v[0:3], v[152:155], v[206:209], v[0:3]
	v_mfma_f32_16x16x32_bf16 v[44:47], v[148:151], v[164:167], v[44:47]
	v_mfma_f32_16x16x32_bf16 v[40:43], v[156:159], v[164:167], v[40:43]
	v_mfma_f32_16x16x32_bf16 v[28:31], v[148:151], v[172:175], v[28:31]
	v_mfma_f32_16x16x32_bf16 v[24:27], v[156:159], v[172:175], v[24:27]
	v_mfma_f32_16x16x32_bf16 v[12:15], v[148:151], v[202:205], v[12:15]
	v_mfma_f32_16x16x32_bf16 v[8:11], v[156:159], v[202:205], v[8:11]
	v_mfma_f32_16x16x32_bf16 v[4:7], v[148:151], v[210:213], v[4:7]
	v_mfma_f32_16x16x32_bf16 v[0:3], v[156:159], v[210:213], v[0:3]
	s_barrier
; #define PG8_STAGE(bufoff, gbase, voff) do { _Pragma("unroll") for (int _i = 0; _i < 2; ++_i) \
;         __builtin_amdgcn_global_load_lds((const unsigned*)((const char*)(gbase) + (voff)[_i]), (LAS unsigned*)(lds + (bufoff) + ldsw + _i * 8192), 16, 0, 0); } while (0)
; #define PG8_LDA(dst, b, h) do { _Pragma("unroll") for (int m = 0; m < 4; ++m) _Pragma("unroll") for (int k = 0; k < 2; ++k) dst[m][k] = *(const LAS bf16x8*)(lds + PG8_SA(b, h) + aoff + m * 2048 + k * 1024); } while (0)
; #define PG8_LDB(dst, b, h) do { _Pragma("unroll") for (int n = 0; n < 2; ++n) _Pragma("unroll") for (int k = 0; k < 2; ++k) dst[n][k] = *(const LAS bf16x8*)(lds + PG8_SB(b, h) + boff + n * 2048 + k * 1024); } while (0)
; #define PG8_MMA(ai, bj, At, Bt) do { __builtin_amdgcn_s_setprio(1); _Pragma("unroll") for (int m = 0; m < 4; ++m) _Pragma("unroll") for (int n = 0; n < 2; ++n) _Pragma("unroll") for (int k = 0; k < 2; ++k) \
;         acc[ai][bj][m][n] = __builtin_amdgcn_mfma_f32_16x16x32_bf16(Bt[n][k], At[m][k], acc[ai][bj][m][n], 0, 0, 0); __builtin_amdgcn_s_setprio(0); } while (0)
; #define PG8_WAIT_V(n) asm volatile("s_waitcnt vmcnt(" #n ")" ::: "memory")
; #define PG8_WAIT_L(n) asm volatile("s_waitcnt lgkmcnt(" #n ")" ::: "memory")
; #define PG8_BAR __builtin_amdgcn_s_barrier()
; #define PG8_SCHED __builtin_amdgcn_sched_barrier(0)
; template <class Epi, class Sched>
; __device__ __forceinline__ void gemm_phase(LAS unsigned char* lds, const Gemm g, const Sched& S, const Epi& E) {
;     ...
;             PG8_LDB(B0, 1, 0); PG8_LDB(B1, 1, 1); PG8_SCHED; PG8_LDA(At, 1, 0); PG8_STAGE(PG8_SA(0, 1), a2 + hstep, voffA);
;             PG8_WAIT_V(8); PG8_WAIT_L(0); PG8_BAR; PG8_MMA(0, 0, At, B0); PG8_MMA(0, 1, At, B1); PG8_BAR; PG8_SCHED;
;             PG8_LDA(At, 1, 1); PG8_STAGE(PG8_SB(1, 0), b3, voffB); PG8_STAGE(PG8_SB(1, 1), b3 + hstep, voffB); PG8_STAGE(PG8_SA(1, 0), a3, voffA);
;             PG8_WAIT_V(8); PG8_WAIT_L(0); PG8_BAR; PG8_MMA(1, 0, At, B0); PG8_MMA(1, 1, At, B1); PG8_BAR; PG8_SCHED;
;         }
;         if (wr == 0) PG8_BAR;
	s_add_i32 s17, 0, 0x18000
	s_add_i32 s33, 0, 0x1c000
	v_add_u32_e32 v140, s17, v231
	v_add_u32_e32 v156, s33, v231
	s_add_u32 s14, s14, s54
	s_addc_u32 s15, s15, 0
	s_mov_b32 m0, s31
	s_nop 0
	global_load_lds_dwordx4 v192, s[14:15]
	s_mov_b32 m0, s34
	s_nop 0
	global_load_lds_dwordx4 v194, s[14:15]
	ds_read_b128 v[128:131], v140
	ds_read_b128 v[132:135], v140 offset:1024
	ds_read_b128 v[136:139], v140 offset:2048
	ds_read_b128 v[140:143], v140 offset:3072
	ds_read_b128 v[144:147], v156
	ds_read_b128 v[148:151], v156 offset:1024
	ds_read_b128 v[152:155], v156 offset:2048
	ds_read_b128 v[156:159], v156 offset:3072
	ds_read_b128 v[160:163], v232 offset:32768
	ds_read_b128 v[164:167], v232 offset:33792
	ds_read_b128 v[168:171], v232 offset:34816
	ds_read_b128 v[172:175], v232 offset:35840
	ds_read_b128 v[176:179], v232 offset:36864
	ds_read_b128 v[202:205], v232 offset:37888
	ds_read_b128 v[206:209], v232 offset:38912
	ds_read_b128 v[210:213], v232 offset:39936
	s_waitcnt vmcnt(8)
	s_waitcnt lgkmcnt(0)
	s_barrier
	s_waitcnt lgkmcnt(0)
	v_mfma_f32_16x16x32_bf16 v[124:127], v[128:131], v[160:163], v[124:127]
	v_mfma_f32_16x16x32_bf16 v[120:123], v[136:139], v[160:163], v[120:123]
	v_mfma_f32_16x16x32_bf16 v[116:119], v[128:131], v[168:171], v[116:119]
	v_mfma_f32_16x16x32_bf16 v[112:115], v[136:139], v[168:171], v[112:115]
	v_mfma_f32_16x16x32_bf16 v[104:107], v[128:131], v[176:179], v[104:107]
	v_mfma_f32_16x16x32_bf16 v[96:99], v[136:139], v[176:179], v[96:99]
	v_mfma_f32_16x16x32_bf16 v[88:91], v[128:131], v[206:209], v[88:91]
	v_mfma_f32_16x16x32_bf16 v[80:83], v[136:139], v[206:209], v[80:83]
	v_mfma_f32_16x16x32_bf16 v[124:127], v[132:135], v[164:167], v[124:127]
	v_mfma_f32_16x16x32_bf16 v[120:123], v[140:143], v[164:167], v[120:123]
	v_mfma_f32_16x16x32_bf16 v[116:119], v[132:135], v[172:175], v[116:119]
	v_mfma_f32_16x16x32_bf16 v[112:115], v[140:143], v[172:175], v[112:115]
	v_mfma_f32_16x16x32_bf16 v[104:107], v[132:135], v[202:205], v[104:107]
	v_mfma_f32_16x16x32_bf16 v[96:99], v[140:143], v[202:205], v[96:99]
	v_mfma_f32_16x16x32_bf16 v[88:91], v[132:135], v[210:213], v[88:91]
	v_mfma_f32_16x16x32_bf16 v[80:83], v[140:143], v[210:213], v[80:83]
	v_mfma_f32_16x16x32_bf16 v[108:111], v[144:147], v[160:163], v[108:111]
	v_mfma_f32_16x16x32_bf16 v[100:103], v[152:155], v[160:163], v[100:103]
	v_mfma_f32_16x16x32_bf16 v[92:95], v[144:147], v[168:171], v[92:95]
	v_mfma_f32_16x16x32_bf16 v[84:87], v[152:155], v[168:171], v[84:87]
	v_mfma_f32_16x16x32_bf16 v[76:79], v[144:147], v[176:179], v[76:79]
	v_mfma_f32_16x16x32_bf16 v[72:75], v[152:155], v[176:179], v[72:75]
	v_mfma_f32_16x16x32_bf16 v[68:71], v[144:147], v[206:209], v[68:71]
	v_mfma_f32_16x16x32_bf16 v[64:67], v[152:155], v[206:209], v[64:67]
	v_mfma_f32_16x16x32_bf16 v[108:111], v[148:151], v[164:167], v[108:111]
	v_mfma_f32_16x16x32_bf16 v[100:103], v[156:159], v[164:167], v[100:103]
	v_mfma_f32_16x16x32_bf16 v[92:95], v[148:151], v[172:175], v[92:95]
	v_mfma_f32_16x16x32_bf16 v[84:87], v[156:159], v[172:175], v[84:87]
	v_mfma_f32_16x16x32_bf16 v[76:79], v[148:151], v[202:205], v[76:79]
	v_mfma_f32_16x16x32_bf16 v[72:75], v[156:159], v[202:205], v[72:75]
	v_mfma_f32_16x16x32_bf16 v[68:71], v[148:151], v[210:213], v[68:71]
	v_mfma_f32_16x16x32_bf16 v[64:67], v[156:159], v[210:213], v[64:67]
	s_barrier
	s_sub_u32 s42, s42, s54
	s_subb_u32 s43, s43, 0
	s_add_u32 s42, s42, 0x80
	s_addc_u32 s43, s43, 0
	s_add_i32 m0, s17, s28
	s_nop 0
	global_load_lds_dwordx4 v184, s[42:43]
	s_add_i32 m0, m0, 0x2000
	s_nop 0
	global_load_lds_dwordx4 v196, s[42:43]
	s_add_u32 s42, s42, s54
	s_addc_u32 s43, s43, 0
	s_add_i32 m0, s33, s28
	s_nop 0
	global_load_lds_dwordx4 v184, s[42:43]
	s_add_i32 m0, m0, 0x2000
	s_nop 0
	global_load_lds_dwordx4 v196, s[42:43]
	s_sub_u32 s14, s14, s54
	s_subb_u32 s15, s15, 0
	s_add_u32 s14, s14, 0x80
	s_addc_u32 s15, s15, 0
	s_mov_b32 m0, s66
	s_nop 0
	global_load_lds_dwordx4 v192, s[14:15]
	s_mov_b32 m0, s67
	s_nop 0
	global_load_lds_dwordx4 v194, s[14:15]
	ds_read_b128 v[160:163], v232 offset:49152
	ds_read_b128 v[164:167], v232 offset:50176
	ds_read_b128 v[168:171], v232 offset:51200
	ds_read_b128 v[172:175], v232 offset:52224
	ds_read_b128 v[176:179], v232 offset:53248
	ds_read_b128 v[202:205], v232 offset:54272
	ds_read_b128 v[206:209], v232 offset:55296
	ds_read_b128 v[210:213], v232 offset:56320
	s_waitcnt vmcnt(8)
	s_waitcnt lgkmcnt(0)
	s_barrier
	s_waitcnt lgkmcnt(0)
	v_mfma_f32_16x16x32_bf16 v[60:63], v[128:131], v[160:163], v[60:63]
	v_mfma_f32_16x16x32_bf16 v[56:59], v[136:139], v[160:163], v[56:59]
	v_mfma_f32_16x16x32_bf16 v[52:55], v[128:131], v[168:171], v[52:55]
	v_mfma_f32_16x16x32_bf16 v[48:51], v[136:139], v[168:171], v[48:51]
	v_mfma_f32_16x16x32_bf16 v[36:39], v[128:131], v[176:179], v[36:39]
	v_mfma_f32_16x16x32_bf16 v[32:35], v[136:139], v[176:179], v[32:35]
	v_mfma_f32_16x16x32_bf16 v[20:23], v[128:131], v[206:209], v[20:23]
	v_mfma_f32_16x16x32_bf16 v[16:19], v[136:139], v[206:209], v[16:19]
	v_mfma_f32_16x16x32_bf16 v[60:63], v[132:135], v[164:167], v[60:63]
	v_mfma_f32_16x16x32_bf16 v[56:59], v[140:143], v[164:167], v[56:59]
	v_mfma_f32_16x16x32_bf16 v[52:55], v[132:135], v[172:175], v[52:55]
	v_mfma_f32_16x16x32_bf16 v[48:51], v[140:143], v[172:175], v[48:51]
	v_mfma_f32_16x16x32_bf16 v[36:39], v[132:135], v[202:205], v[36:39]
	v_mfma_f32_16x16x32_bf16 v[32:35], v[140:143], v[202:205], v[32:35]
	v_mfma_f32_16x16x32_bf16 v[20:23], v[132:135], v[210:213], v[20:23]
	v_mfma_f32_16x16x32_bf16 v[16:19], v[140:143], v[210:213], v[16:19]
	v_mfma_f32_16x16x32_bf16 v[44:47], v[144:147], v[160:163], v[44:47]
	v_mfma_f32_16x16x32_bf16 v[40:43], v[152:155], v[160:163], v[40:43]
	v_mfma_f32_16x16x32_bf16 v[28:31], v[144:147], v[168:171], v[28:31]
	v_mfma_f32_16x16x32_bf16 v[24:27], v[152:155], v[168:171], v[24:27]
	v_mfma_f32_16x16x32_bf16 v[12:15], v[144:147], v[176:179], v[12:15]
	v_mfma_f32_16x16x32_bf16 v[8:11], v[152:155], v[176:179], v[8:11]
	v_mfma_f32_16x16x32_bf16 v[4:7], v[144:147], v[206:209], v[4:7]
	v_mfma_f32_16x16x32_bf16 v[0:3], v[152:155], v[206:209], v[0:3]
	v_mfma_f32_16x16x32_bf16 v[44:47], v[148:151], v[164:167], v[44:47]
	v_mfma_f32_16x16x32_bf16 v[40:43], v[156:159], v[164:167], v[40:43]
	v_mfma_f32_16x16x32_bf16 v[28:31], v[148:151], v[172:175], v[28:31]
	v_mfma_f32_16x16x32_bf16 v[24:27], v[156:159], v[172:175], v[24:27]
	v_mfma_f32_16x16x32_bf16 v[12:15], v[148:151], v[202:205], v[12:15]
	v_mfma_f32_16x16x32_bf16 v[8:11], v[156:159], v[202:205], v[8:11]
	v_mfma_f32_16x16x32_bf16 v[4:7], v[148:151], v[210:213], v[4:7]
	v_mfma_f32_16x16x32_bf16 v[0:3], v[156:159], v[210:213], v[0:3]
	s_barrier
	s_add_u32 s6, s6, 0x100
	s_addc_u32 s7, s7, 0
	s_add_u32 s13, s13, 0x100
	s_addc_u32 s16, s16, 0
	s_cmp_ge_u32 s19, s8
	s_mov_b32 s17, s19
	s_cbranch_scc0 .LBB0_599
	s_setprio 0
	s_and_b64 vcc, exec, s[62:63]
	s_cbranch_vccz .LBB0_602
	s_barrier

; #define PG8_STAGE(bufoff, gbase, voff) do { _Pragma("unroll") for (int _i = 0; _i < 2; ++_i) \
;         __builtin_amdgcn_global_load_lds((const unsigned*)((const char*)(gbase) + (voff)[_i]), (LAS unsigned*)(lds + (bufoff) + ldsw + _i * 8192), 16, 0, 0); } while (0)
; #define PG8_LDA(dst, b, h) do { _Pragma("unroll") for (int m = 0; m < 4; ++m) _Pragma("unroll") for (int k = 0; k < 2; ++k) dst[m][k] = *(const LAS bf16x8*)(lds + PG8_SA(b, h) + aoff + m * 2048 + k * 1024); } while (0)
; #define PG8_LDB(dst, b, h) do { _Pragma("unroll") for (int n = 0; n < 2; ++n) _Pragma("unroll") for (int k = 0; k < 2; ++k) dst[n][k] = *(const LAS bf16x8*)(lds + PG8_SB(b, h) + boff + n * 2048 + k * 1024); } while (0)
; #define PG8_MMA(ai, bj, At, Bt) do { __builtin_amdgcn_s_setprio(1); _Pragma("unroll") for (int m = 0; m < 4; ++m) _Pragma("unroll") for (int n = 0; n < 2; ++n) _Pragma("unroll") for (int k = 0; k < 2; ++k) \
;         acc[ai][bj][m][n] = __builtin_amdgcn_mfma_f32_16x16x32_bf16(Bt[n][k], At[m][k], acc[ai][bj][m][n], 0, 0, 0); __builtin_amdgcn_s_setprio(0); } while (0)
; #define PG8_WAIT_V(n) asm volatile("s_waitcnt vmcnt(" #n ")" ::: "memory")
; #define PG8_WAIT_L(n) asm volatile("s_waitcnt lgkmcnt(" #n ")" ::: "memory")
; #define PG8_BAR __builtin_amdgcn_s_barrier()
; #define PG8_SCHED __builtin_amdgcn_sched_barrier(0)
; template <class Epi, class Sched>
; __device__ __forceinline__ void gemm_phase(LAS unsigned char* lds, const Gemm g, const Sched& S, const Epi& E) {
;     ...
;         for (int t = 0; t < nt; t += 2) {
;             const bool last = (t == nt - 2);
;             const char* a1 = cA + (size_t)(t + 1) * kstep;
;             const char* a2 = last ? nA : cA + (size_t)(t + 2) * kstep; const char* b2 = last ? nB : cB + (size_t)(t + 2) * kstep;
;             const char* a3 = a2 + kstep; const char* b3 = b2 + kstep;
;             PG8_LDB(B0, 0, 0); PG8_LDB(B1, 0, 1); PG8_SCHED; PG8_LDA(At, 0, 0); PG8_STAGE(PG8_SA(1, 1), a1 + hstep, voffA);
;             PG8_WAIT_V(8); PG8_WAIT_L(0); PG8_BAR; PG8_MMA(0, 0, At, B0); PG8_MMA(0, 1, At, B1); PG8_BAR; PG8_SCHED;
;             PG8_LDA(At, 0, 1); PG8_STAGE(PG8_SB(0, 0), b2, voffB); PG8_STAGE(PG8_SB(0, 1), b2 + hstep, voffB); PG8_STAGE(PG8_SA(0, 0), a2, voffA);
;             PG8_WAIT_V(8); PG8_WAIT_L(0); PG8_BAR; PG8_MMA(1, 0, At, B0); PG8_MMA(1, 1, At, B1); PG8_BAR; PG8_SCHED;
.LBB0_744:
	s_add_u32 s24, s22, 0xfffc0080
	s_addc_u32 s25, s23, -1
	s_add_i32 s49, 0, 0x10000
	s_cmp_eq_u32 s48, 12
	s_cselect_b32 s27, s15, s25
	s_cselect_b32 s26, s44, s24
	s_cselect_b32 s25, s17, s47
	s_cselect_b32 s24, s45, s46
	s_add_i32 s52, 0, 0x14000
	v_add_u32_e32 v140, s49, v162
	v_add_u32_e32 v158, s52, v162
	s_add_i32 m0, s28, 0xc000
	s_nop 0
	global_load_lds_dwordx4 v150, s[22:23]
	s_add_i32 m0, s28, 0xe000
	s_nop 0
	global_load_lds_dwordx4 v152, s[22:23]
	ds_read_b128 v[128:131], v140
	ds_read_b128 v[132:135], v140 offset:1024
	ds_read_b128 v[136:139], v140 offset:2048
	ds_read_b128 v[140:143], v140 offset:3072
	ds_read_b128 v[154:157], v158
	ds_read_b128 v[164:167], v158 offset:1024
	ds_read_b128 v[168:171], v158 offset:2048
	ds_read_b128 v[172:175], v158 offset:3072
	ds_read_b128 v[176:179], v163
	ds_read_b128 v[192:195], v163 offset:1024
	ds_read_b128 v[196:199], v163 offset:2048
	ds_read_b128 v[200:203], v163 offset:3072
	ds_read_b128 v[204:207], v163 offset:4096
	ds_read_b128 v[208:211], v163 offset:5120
	ds_read_b128 v[212:215], v163 offset:6144
	ds_read_b128 v[230:233], v163 offset:7168
	s_waitcnt vmcnt(8)
	s_waitcnt lgkmcnt(0)
	s_barrier
	s_waitcnt lgkmcnt(0)
	v_mfma_f32_16x16x32_bf16 v[124:127], v[128:131], v[176:179], v[124:127]
	v_mfma_f32_16x16x32_bf16 v[120:123], v[136:139], v[176:179], v[120:123]
	v_mfma_f32_16x16x32_bf16 v[108:111], v[128:131], v[196:199], v[108:111]
	v_mfma_f32_16x16x32_bf16 v[104:107], v[136:139], v[196:199], v[104:107]
	v_mfma_f32_16x16x32_bf16 v[92:95], v[128:131], v[204:207], v[92:95]
	v_mfma_f32_16x16x32_bf16 v[88:91], v[136:139], v[204:207], v[88:91]
	v_mfma_f32_16x16x32_bf16 v[76:79], v[128:131], v[212:215], v[76:79]
	v_mfma_f32_16x16x32_bf16 v[72:75], v[136:139], v[212:215], v[72:75]
	v_mfma_f32_16x16x32_bf16 v[124:127], v[132:135], v[192:195], v[124:127]
	v_mfma_f32_16x16x32_bf16 v[120:123], v[140:143], v[192:195], v[120:123]
	v_mfma_f32_16x16x32_bf16 v[108:111], v[132:135], v[200:203], v[108:111]
	v_mfma_f32_16x16x32_bf16 v[104:107], v[140:143], v[200:203], v[104:107]
	v_mfma_f32_16x16x32_bf16 v[92:95], v[132:135], v[208:211], v[92:95]
	v_mfma_f32_16x16x32_bf16 v[88:91], v[140:143], v[208:211], v[88:91]
	v_mfma_f32_16x16x32_bf16 v[76:79], v[132:135], v[230:233], v[76:79]
	v_mfma_f32_16x16x32_bf16 v[72:75], v[140:143], v[230:233], v[72:75]
	v_mfma_f32_16x16x32_bf16 v[112:115], v[154:157], v[176:179], v[112:115]
	v_mfma_f32_16x16x32_bf16 v[116:119], v[168:171], v[176:179], v[116:119]
	v_mfma_f32_16x16x32_bf16 v[96:99], v[154:157], v[196:199], v[96:99]
	v_mfma_f32_16x16x32_bf16 v[100:103], v[168:171], v[196:199], v[100:103]
	v_mfma_f32_16x16x32_bf16 v[80:83], v[154:157], v[204:207], v[80:83]
	v_mfma_f32_16x16x32_bf16 v[84:87], v[168:171], v[204:207], v[84:87]
	v_mfma_f32_16x16x32_bf16 v[64:67], v[154:157], v[212:215], v[64:67]
	v_mfma_f32_16x16x32_bf16 v[68:71], v[168:171], v[212:215], v[68:71]
	v_mfma_f32_16x16x32_bf16 v[112:115], v[164:167], v[192:195], v[112:115]
	v_mfma_f32_16x16x32_bf16 v[116:119], v[172:175], v[192:195], v[116:119]
	v_mfma_f32_16x16x32_bf16 v[96:99], v[164:167], v[200:203], v[96:99]
	v_mfma_f32_16x16x32_bf16 v[100:103], v[172:175], v[200:203], v[100:103]
	v_mfma_f32_16x16x32_bf16 v[80:83], v[164:167], v[208:211], v[80:83]
	v_mfma_f32_16x16x32_bf16 v[84:87], v[172:175], v[208:211], v[84:87]
	v_mfma_f32_16x16x32_bf16 v[64:67], v[164:167], v[230:233], v[64:67]
	v_mfma_f32_16x16x32_bf16 v[68:71], v[172:175], v[230:233], v[68:71]
	s_barrier
	s_add_i32 s49, s49, s8
	s_mov_b32 m0, s49
	s_nop 0
	global_load_lds_dwordx4 v184, s[24:25]
	s_add_i32 m0, s49, 0x2000
	s_add_u32 s50, s24, 0x40000
	s_addc_u32 s51, s25, 0
	s_add_i32 s49, s52, s8
	global_load_lds_dwordx4 v144, s[24:25]
	s_mov_b32 m0, s49
	s_nop 0
	global_load_lds_dwordx4 v184, s[50:51]
	s_add_i32 m0, s49, 0x2000
	s_nop 0
	global_load_lds_dwordx4 v144, s[50:51]
	s_mov_b32 m0, s28
	s_nop 0
	global_load_lds_dwordx4 v148, s[26:27]
	s_mov_b32 m0, s29
	s_nop 0
	global_load_lds_dwordx4 v146, s[26:27]
	ds_read_b128 v[176:179], v163 offset:16384
	ds_read_b128 v[192:195], v163 offset:17408
	ds_read_b128 v[196:199], v163 offset:18432
	ds_read_b128 v[200:203], v163 offset:19456
	ds_read_b128 v[204:207], v163 offset:20480
	ds_read_b128 v[208:211], v163 offset:21504
	ds_read_b128 v[212:215], v163 offset:22528
	ds_read_b128 v[230:233], v163 offset:23552
	s_waitcnt vmcnt(8)
	s_waitcnt lgkmcnt(0)
	s_barrier
	s_waitcnt lgkmcnt(0)
	v_mfma_f32_16x16x32_bf16 v[60:63], v[128:131], v[176:179], v[60:63]
	v_mfma_f32_16x16x32_bf16 v[56:59], v[136:139], v[176:179], v[56:59]
	v_mfma_f32_16x16x32_bf16 v[44:47], v[128:131], v[196:199], v[44:47]
	v_mfma_f32_16x16x32_bf16 v[40:43], v[136:139], v[196:199], v[40:43]
	v_mfma_f32_16x16x32_bf16 v[28:31], v[128:131], v[204:207], v[28:31]
	v_mfma_f32_16x16x32_bf16 v[24:27], v[136:139], v[204:207], v[24:27]
	v_mfma_f32_16x16x32_bf16 v[12:15], v[128:131], v[212:215], v[12:15]
	v_mfma_f32_16x16x32_bf16 v[8:11], v[136:139], v[212:215], v[8:11]
	v_mfma_f32_16x16x32_bf16 v[60:63], v[132:135], v[192:195], v[60:63]
	v_mfma_f32_16x16x32_bf16 v[56:59], v[140:143], v[192:195], v[56:59]
	v_mfma_f32_16x16x32_bf16 v[44:47], v[132:135], v[200:203], v[44:47]
	v_mfma_f32_16x16x32_bf16 v[40:43], v[140:143], v[200:203], v[40:43]
	v_mfma_f32_16x16x32_bf16 v[28:31], v[132:135], v[208:211], v[28:31]
	v_mfma_f32_16x16x32_bf16 v[24:27], v[140:143], v[208:211], v[24:27]
	v_mfma_f32_16x16x32_bf16 v[12:15], v[132:135], v[230:233], v[12:15]
	v_mfma_f32_16x16x32_bf16 v[8:11], v[140:143], v[230:233], v[8:11]
	v_mfma_f32_16x16x32_bf16 v[48:51], v[154:157], v[176:179], v[48:51]
	v_mfma_f32_16x16x32_bf16 v[52:55], v[168:171], v[176:179], v[52:55]
	v_mfma_f32_16x16x32_bf16 v[32:35], v[154:157], v[196:199], v[32:35]
	v_mfma_f32_16x16x32_bf16 v[36:39], v[168:171], v[196:199], v[36:39]
	v_mfma_f32_16x16x32_bf16 v[16:19], v[154:157], v[204:207], v[16:19]
	v_mfma_f32_16x16x32_bf16 v[20:23], v[168:171], v[204:207], v[20:23]
	v_mfma_f32_16x16x32_bf16 v[0:3], v[154:157], v[212:215], v[0:3]
	v_mfma_f32_16x16x32_bf16 v[4:7], v[168:171], v[212:215], v[4:7]
	v_mfma_f32_16x16x32_bf16 v[48:51], v[164:167], v[192:195], v[48:51]
	v_mfma_f32_16x16x32_bf16 v[52:55], v[172:175], v[192:195], v[52:55]
	v_mfma_f32_16x16x32_bf16 v[32:35], v[164:167], v[200:203], v[32:35]
	v_mfma_f32_16x16x32_bf16 v[36:39], v[172:175], v[200:203], v[36:39]
	v_mfma_f32_16x16x32_bf16 v[16:19], v[164:167], v[208:211], v[16:19]
	v_mfma_f32_16x16x32_bf16 v[20:23], v[172:175], v[208:211], v[20:23]
	v_mfma_f32_16x16x32_bf16 v[0:3], v[164:167], v[230:233], v[0:3]
	v_mfma_f32_16x16x32_bf16 v[4:7], v[172:175], v[230:233], v[4:7]
	s_barrier
; #define PG8_STAGE(bufoff, gbase, voff) do { _Pragma("unroll") for (int _i = 0; _i < 2; ++_i) \
;         __builtin_amdgcn_global_load_lds((const unsigned*)((const char*)(gbase) + (voff)[_i]), (LAS unsigned*)(lds + (bufoff) + ldsw + _i * 8192), 16, 0, 0); } while (0)
; #define PG8_LDA(dst, b, h) do { _Pragma("unroll") for (int m = 0; m < 4; ++m) _Pragma("unroll") for (int k = 0; k < 2; ++k) dst[m][k] = *(const LAS bf16x8*)(lds + PG8_SA(b, h) + aoff + m * 2048 + k * 1024); } while (0)
; #define PG8_LDB(dst, b, h) do { _Pragma("unroll") for (int n = 0; n < 2; ++n) _Pragma("unroll") for (int k = 0; k < 2; ++k) dst[n][k] = *(const LAS bf16x8*)(lds + PG8_SB(b, h) + boff + n * 2048 + k * 1024); } while (0)
; #define PG8_MMA(ai, bj, At, Bt) do { __builtin_amdgcn_s_setprio(1); _Pragma("unroll") for (int m = 0; m < 4; ++m) _Pragma("unroll") for (int n = 0; n < 2; ++n) _Pragma("unroll") for (int k = 0; k < 2; ++k) \
;         acc[ai][bj][m][n] = __builtin_amdgcn_mfma_f32_16x16x32_bf16(Bt[n][k], At[m][k], acc[ai][bj][m][n], 0, 0, 0); __builtin_amdgcn_s_setprio(0); } while (0)
; #define PG8_WAIT_V(n) asm volatile("s_waitcnt vmcnt(" #n ")" ::: "memory")
; #define PG8_WAIT_L(n) asm volatile("s_waitcnt lgkmcnt(" #n ")" ::: "memory")
; #define PG8_BAR __builtin_amdgcn_s_barrier()
; #define PG8_SCHED __builtin_amdgcn_sched_barrier(0)
; template <class Epi, class Sched>
; __device__ __forceinline__ void gemm_phase(LAS unsigned char* lds, const Gemm g, const Sched& S, const Epi& E) {
;     ...
;             PG8_LDB(B0, 1, 0); PG8_LDB(B1, 1, 1); PG8_SCHED; PG8_LDA(At, 1, 0); PG8_STAGE(PG8_SA(0, 1), a2 + hstep, voffA);
;             PG8_WAIT_V(8); PG8_WAIT_L(0); PG8_BAR; PG8_MMA(0, 0, At, B0); PG8_MMA(0, 1, At, B1); PG8_BAR; PG8_SCHED;
;             PG8_LDA(At, 1, 1); PG8_STAGE(PG8_SB(1, 0), b3, voffB); PG8_STAGE(PG8_SB(1, 1), b3 + hstep, voffB); PG8_STAGE(PG8_SA(1, 0), a3, voffA);
;             PG8_WAIT_V(8); PG8_WAIT_L(0); PG8_BAR; PG8_MMA(1, 0, At, B0); PG8_MMA(1, 1, At, B1); PG8_BAR; PG8_SCHED;
;         }
;         if (wr == 0) PG8_BAR;
	s_add_i32 s49, 0, 0x18000
	s_add_i32 s50, 0, 0x1c000
	v_add_u32_e32 v140, s49, v162
	v_add_u32_e32 v172, s50, v162
	s_add_u32 s26, s26, 0x40000
	s_addc_u32 s27, s27, 0
	s_mov_b32 m0, s30
	s_nop 0
	global_load_lds_dwordx4 v148, s[26:27]
	s_mov_b32 m0, s31
	s_nop 0
	global_load_lds_dwordx4 v146, s[26:27]
	ds_read_b128 v[128:131], v140
	ds_read_b128 v[132:135], v140 offset:1024
	ds_read_b128 v[136:139], v140 offset:2048
	ds_read_b128 v[140:143], v140 offset:3072
	ds_read_b128 v[154:157], v172
	ds_read_b128 v[164:167], v172 offset:1024
	ds_read_b128 v[168:171], v172 offset:2048
	ds_read_b128 v[172:175], v172 offset:3072
	ds_read_b128 v[176:179], v163 offset:32768
	ds_read_b128 v[192:195], v163 offset:33792
	ds_read_b128 v[196:199], v163 offset:34816
	ds_read_b128 v[200:203], v163 offset:35840
	ds_read_b128 v[204:207], v163 offset:36864
	ds_read_b128 v[208:211], v163 offset:37888
	ds_read_b128 v[212:215], v163 offset:38912
	ds_read_b128 v[230:233], v163 offset:39936
	s_waitcnt vmcnt(8)
	s_waitcnt lgkmcnt(0)
	s_barrier
	s_waitcnt lgkmcnt(0)
	v_mfma_f32_16x16x32_bf16 v[124:127], v[128:131], v[176:179], v[124:127]
	v_mfma_f32_16x16x32_bf16 v[120:123], v[136:139], v[176:179], v[120:123]
	v_mfma_f32_16x16x32_bf16 v[108:111], v[128:131], v[196:199], v[108:111]
	v_mfma_f32_16x16x32_bf16 v[104:107], v[136:139], v[196:199], v[104:107]
	v_mfma_f32_16x16x32_bf16 v[92:95], v[128:131], v[204:207], v[92:95]
	v_mfma_f32_16x16x32_bf16 v[88:91], v[136:139], v[204:207], v[88:91]
	v_mfma_f32_16x16x32_bf16 v[76:79], v[128:131], v[212:215], v[76:79]
	v_mfma_f32_16x16x32_bf16 v[72:75], v[136:139], v[212:215], v[72:75]
	v_mfma_f32_16x16x32_bf16 v[124:127], v[132:135], v[192:195], v[124:127]
	v_mfma_f32_16x16x32_bf16 v[120:123], v[140:143], v[192:195], v[120:123]
	v_mfma_f32_16x16x32_bf16 v[108:111], v[132:135], v[200:203], v[108:111]
	v_mfma_f32_16x16x32_bf16 v[104:107], v[140:143], v[200:203], v[104:107]
	v_mfma_f32_16x16x32_bf16 v[92:95], v[132:135], v[208:211], v[92:95]
	v_mfma_f32_16x16x32_bf16 v[88:91], v[140:143], v[208:211], v[88:91]
	v_mfma_f32_16x16x32_bf16 v[76:79], v[132:135], v[230:233], v[76:79]
	v_mfma_f32_16x16x32_bf16 v[72:75], v[140:143], v[230:233], v[72:75]
	v_mfma_f32_16x16x32_bf16 v[112:115], v[154:157], v[176:179], v[112:115]
	v_mfma_f32_16x16x32_bf16 v[116:119], v[168:171], v[176:179], v[116:119]
	v_mfma_f32_16x16x32_bf16 v[96:99], v[154:157], v[196:199], v[96:99]
	v_mfma_f32_16x16x32_bf16 v[100:103], v[168:171], v[196:199], v[100:103]
	v_mfma_f32_16x16x32_bf16 v[80:83], v[154:157], v[204:207], v[80:83]
	v_mfma_f32_16x16x32_bf16 v[84:87], v[168:171], v[204:207], v[84:87]
	v_mfma_f32_16x16x32_bf16 v[64:67], v[154:157], v[212:215], v[64:67]
	v_mfma_f32_16x16x32_bf16 v[68:71], v[168:171], v[212:215], v[68:71]
	v_mfma_f32_16x16x32_bf16 v[112:115], v[164:167], v[192:195], v[112:115]
	v_mfma_f32_16x16x32_bf16 v[116:119], v[172:175], v[192:195], v[116:119]
	v_mfma_f32_16x16x32_bf16 v[96:99], v[164:167], v[200:203], v[96:99]
	v_mfma_f32_16x16x32_bf16 v[100:103], v[172:175], v[200:203], v[100:103]
	v_mfma_f32_16x16x32_bf16 v[80:83], v[164:167], v[208:211], v[80:83]
	v_mfma_f32_16x16x32_bf16 v[84:87], v[172:175], v[208:211], v[84:87]
	v_mfma_f32_16x16x32_bf16 v[64:67], v[164:167], v[230:233], v[64:67]
	v_mfma_f32_16x16x32_bf16 v[68:71], v[172:175], v[230:233], v[68:71]
	s_barrier
	s_add_u32 s24, s24, 0x80
	s_addc_u32 s25, s25, 0
	s_add_i32 m0, s49, s8
	s_nop 0
	global_load_lds_dwordx4 v184, s[24:25]
	s_add_i32 m0, m0, 0x2000
	s_nop 0
	global_load_lds_dwordx4 v144, s[24:25]
	s_add_u32 s24, s24, 0x40000
	s_addc_u32 s25, s25, 0
	s_add_i32 m0, s50, s8
	s_nop 0
	global_load_lds_dwordx4 v184, s[24:25]
	s_add_i32 m0, m0, 0x2000
	s_nop 0
	global_load_lds_dwordx4 v144, s[24:25]
	s_add_u32 s26, s26, 0xfffc0080
	s_addc_u32 s27, s27, -1
	s_mov_b32 m0, s36
	s_nop 0
	global_load_lds_dwordx4 v148, s[26:27]
	s_mov_b32 m0, s37
	s_nop 0
	global_load_lds_dwordx4 v146, s[26:27]
	ds_read_b128 v[176:179], v163 offset:49152
	ds_read_b128 v[192:195], v163 offset:50176
	ds_read_b128 v[196:199], v163 offset:51200
	ds_read_b128 v[200:203], v163 offset:52224
	ds_read_b128 v[204:207], v163 offset:53248
	ds_read_b128 v[208:211], v163 offset:54272
	ds_read_b128 v[212:215], v163 offset:55296
	ds_read_b128 v[230:233], v163 offset:56320
	s_waitcnt vmcnt(8)
	s_waitcnt lgkmcnt(0)
	s_barrier
	s_waitcnt lgkmcnt(0)
	v_mfma_f32_16x16x32_bf16 v[60:63], v[128:131], v[176:179], v[60:63]
	v_mfma_f32_16x16x32_bf16 v[56:59], v[136:139], v[176:179], v[56:59]
	v_mfma_f32_16x16x32_bf16 v[44:47], v[128:131], v[196:199], v[44:47]
	v_mfma_f32_16x16x32_bf16 v[40:43], v[136:139], v[196:199], v[40:43]
	v_mfma_f32_16x16x32_bf16 v[28:31], v[128:131], v[204:207], v[28:31]
	v_mfma_f32_16x16x32_bf16 v[24:27], v[136:139], v[204:207], v[24:27]
	v_mfma_f32_16x16x32_bf16 v[12:15], v[128:131], v[212:215], v[12:15]
	v_mfma_f32_16x16x32_bf16 v[8:11], v[136:139], v[212:215], v[8:11]
	v_mfma_f32_16x16x32_bf16 v[60:63], v[132:135], v[192:195], v[60:63]
	v_mfma_f32_16x16x32_bf16 v[56:59], v[140:143], v[192:195], v[56:59]
	v_mfma_f32_16x16x32_bf16 v[44:47], v[132:135], v[200:203], v[44:47]
	v_mfma_f32_16x16x32_bf16 v[40:43], v[140:143], v[200:203], v[40:43]
	v_mfma_f32_16x16x32_bf16 v[28:31], v[132:135], v[208:211], v[28:31]
	v_mfma_f32_16x16x32_bf16 v[24:27], v[140:143], v[208:211], v[24:27]
	v_mfma_f32_16x16x32_bf16 v[12:15], v[132:135], v[230:233], v[12:15]
	v_mfma_f32_16x16x32_bf16 v[8:11], v[140:143], v[230:233], v[8:11]
	v_mfma_f32_16x16x32_bf16 v[48:51], v[154:157], v[176:179], v[48:51]
	v_mfma_f32_16x16x32_bf16 v[52:55], v[168:171], v[176:179], v[52:55]
	v_mfma_f32_16x16x32_bf16 v[32:35], v[154:157], v[196:199], v[32:35]
	v_mfma_f32_16x16x32_bf16 v[36:39], v[168:171], v[196:199], v[36:39]
	v_mfma_f32_16x16x32_bf16 v[16:19], v[154:157], v[204:207], v[16:19]
	v_mfma_f32_16x16x32_bf16 v[20:23], v[168:171], v[204:207], v[20:23]
	v_mfma_f32_16x16x32_bf16 v[0:3], v[154:157], v[212:215], v[0:3]
	v_mfma_f32_16x16x32_bf16 v[4:7], v[168:171], v[212:215], v[4:7]
	v_mfma_f32_16x16x32_bf16 v[48:51], v[164:167], v[192:195], v[48:51]
	v_mfma_f32_16x16x32_bf16 v[52:55], v[172:175], v[192:195], v[52:55]
	v_mfma_f32_16x16x32_bf16 v[32:35], v[164:167], v[200:203], v[32:35]
	v_mfma_f32_16x16x32_bf16 v[36:39], v[172:175], v[200:203], v[36:39]
	v_mfma_f32_16x16x32_bf16 v[16:19], v[164:167], v[208:211], v[16:19]
	v_mfma_f32_16x16x32_bf16 v[20:23], v[172:175], v[208:211], v[20:23]
	v_mfma_f32_16x16x32_bf16 v[0:3], v[164:167], v[230:233], v[0:3]
	v_mfma_f32_16x16x32_bf16 v[4:7], v[172:175], v[230:233], v[4:7]
	s_barrier
	s_add_i32 s48, s48, 2
	s_add_u32 s22, s22, 0x100
	s_addc_u32 s23, s23, 0
	s_add_u32 s46, s46, 0x100
	s_addc_u32 s47, s47, 0
	s_cmp_gt_u32 s48, 13
	s_cbranch_scc0 .LBB0_744
	s_setprio 0
	s_and_b64 vcc, exec, s[6:7]
	s_cbranch_vccz .LBB0_747
	s_barrier
